# wide conversion routine; the second half of HG_IN is converted by the converting half of the split stage instead of by the GEMM half after its units
# baseline (speedup 1.0000x reference)
; #define PG8_LAS __attribute__((address_space(3)))
; __global__ void __launch_bounds__(NTHREADS, 2) fwd_kernel(Args args) {
;     ...
;             else { pg8::Gemm g_{(const pg8::bf16_t*)FW(F, WS_H), (const pg8::bf16_t*)FW(F, WS_W_NSA_IN), MTOK, NSA_NP, DM, DM, 0}; SchedP S_{xg * 16 + li, ctl + CW_PF, barw};
;                 pg8::EpiBf16RS E_{(pg8::bf16_t*)FW(F, WS_PROJ), NSA_NP, (const float*)FW(F, WS_MISC + MISC_RS)};
;                 pg8::gemm_phase<pg8::EpiBf16RS, SchedP, true, true>((PG8_LAS unsigned char*)lds + RING_OFF, g_, S_, E_);
;                 __syncthreads(); p0_split_tail(F, xg * 16 + li, 128); }
.LBB0_260:
	v_readlane_b32 s4, v254, 7
	v_readlane_b32 s5, v254, 8
	s_waitcnt vmcnt(0)
	s_barrier
	s_barrier
	s_mov_b64 s[0:1], 0

; __device__ __forceinline__ void p0_split_tail(Frame& F, int my, int nconv) {
;     const int gw0 = F.gw, ngw0 = F.ngw; F.gw = my * NWAVES + F.wave; F.ngw = nconv * NWAVES;
;     int it0 = 0;
;     p0_transpose_matrix2(F, FIN(F, 15), DM, HG_NP, (bf16*)FW(F, WS_W_HG_IN), HG_NP / 32 - P_HG_SPLIT, [](int nb) { return (P_HG_SPLIT + nb) * 32; }, [](int nb) { return (P_HG_SPLIT + nb) * 32; }, it0, FIN(F, 1) + 2 * DM);
;     F.gw = gw0; F.ngw = ngw0;
; }
; __device__ __forceinline__ void p0_split_convert(Frame& F, int my, int nconv, unsigned* flag) {
;     ...
;     p0_transpose_matrix(F, FIN(F, 15), DM, HG_NP, (bf16*)FW(F, WS_W_HG_IN), P_HG_SPLIT, [](int nb) { return nb * 32; }, it0, FIN(F, 1) + 2 * DM);
.Lcv_ret3:
	v_readlane_b32 s62, v254, 7
	v_readlane_b32 s63, v254, 8
	s_nop 3
	s_load_dwordx2 s[44:45], s[62:63], 0x78
	s_load_dwordx2 s[52:53], s[62:63], 0x8
	s_waitcnt lgkmcnt(0)
	s_add_u32 s52, s52, 0x8000
	s_addc_u32 s53, s53, 0
	s_mov_b32 s46, 0x10000
	s_mov_b32 s47, 0
	s_add_u32 s48, s70, 0x15600000
	s_addc_u32 s49, s71, 0
	s_mov_b32 s50, 128
	s_mov_b32 s51, 0x8
	s_mov_b32 s54, 0
	s_mov_b32 s55, 640
	s_mov_b32 s56, s19
	s_mov_b32 s32, 4
	s_branch .Lcva_run

; template <class CM, class RM>
; __device__ __forceinline__ void p0_transpose_matrix2(Frame& F, const float* W, int K, int N, bf16* WT, int nblk, CM colmap, RM rowmap, int& it0, const float* kgain = nullptr) {
;     ...
;     for (int r = first; r < nitems; r += F.ngw) {
;         const int kb = r / nblk, nb = r % nblk;
;         p0_transpose_item(W, K, N, WT, kb, colmap(nb), rowmap(nb), scr, F.lane, kgain);
;     }
;     it0 += nitems;
.Lcva_exit:
	s_waitcnt vmcnt(0)
	s_cmp_eq_u32 s32, 1
	s_cbranch_scc1 .Lcv_ret1
	s_cmp_eq_u32 s32, 2
	s_cbranch_scc1 .Lcv_ret2
	s_cmp_eq_u32 s32, 3
	s_cbranch_scc1 .Lcv_ret3
	s_branch .Lcv_ret4
